# gates remainder round on the sample panels (unit order remap) on top of the fused-epilogue permlane reductions
# speedup vs baseline: 1.0027x; 1.0027x over previous
.Lgmap_done:
.LBB0_457:
	s_ashr_i32 s57, s56, 31
	s_lshl_b64 s[8:9], s[56:57], 19
	s_add_u32 s1, s30, s8
	s_addc_u32 s16, s31, s9
	s_ashr_i32 s8, s46, 1
	s_ashr_i32 s9, s8, 31
	s_lshl_b64 s[8:9], s[8:9], 9
	s_add_u32 s72, s1, s8
	s_addc_u32 s73, s16, s9
	s_and_b64 s[8:9], s[44:45], exec
	s_cselect_b32 s1, s73, s83
	s_cselect_b32 s16, s72, s82
	s_ashr_i32 s47, s46, 31
	s_lshl_b64 s[8:9], s[46:47], 17
	s_add_u32 s74, s3, s8
	s_addc_u32 s75, s27, s9
	s_and_b64 s[8:9], s[44:45], exec
	v_mov_b32_e32 v0, 0
	s_cselect_b32 s17, s75, s81
	s_cselect_b32 s28, s74, s80
	s_mov_b32 s18, 0
	s_mov_b64 s[84:85], -1
	s_mov_b64 s[36:37], 0
	v_mov_b32_e32 v28, 0
	v_mov_b32_e32 v29, 0
	v_mov_b32_e32 v30, 0
	v_mov_b32_e32 v31, 0
	s_nop 1
	v_mfma_f32_16x16x32_bf16 v[0:3], v[28:31], v[28:31], 0
	v_mfma_f32_16x16x32_bf16 v[4:7], v[28:31], v[28:31], 0
	v_mfma_f32_16x16x32_bf16 v[8:11], v[28:31], v[28:31], 0
	v_mfma_f32_16x16x32_bf16 v[12:15], v[28:31], v[28:31], 0
	v_mfma_f32_16x16x32_bf16 v[16:19], v[28:31], v[28:31], 0
	v_mfma_f32_16x16x32_bf16 v[20:23], v[28:31], v[28:31], 0
	v_mfma_f32_16x16x32_bf16 v[24:27], v[28:31], v[28:31], 0
	v_mfma_f32_16x16x32_bf16 v[36:39], v[28:31], v[28:31], 0
	v_mfma_f32_16x16x32_bf16 v[48:51], v[28:31], v[28:31], 0
	v_mfma_f32_16x16x32_bf16 v[52:55], v[28:31], v[28:31], 0
	v_mfma_f32_16x16x32_bf16 v[56:59], v[28:31], v[28:31], 0
	v_mfma_f32_16x16x32_bf16 v[60:63], v[28:31], v[28:31], 0
	v_mfma_f32_16x16x32_bf16 v[64:67], v[28:31], v[28:31], 0
	v_mfma_f32_16x16x32_bf16 v[68:71], v[28:31], v[28:31], 0
	v_mfma_f32_16x16x32_bf16 v[72:75], v[28:31], v[28:31], 0
	v_mfma_f32_16x16x32_bf16 v[76:79], v[28:31], v[28:31], 0
	v_mfma_f32_16x16x32_bf16 v[80:83], v[28:31], v[28:31], 0
	v_mfma_f32_16x16x32_bf16 v[84:87], v[28:31], v[28:31], 0
	v_mfma_f32_16x16x32_bf16 v[88:91], v[28:31], v[28:31], 0
	v_mfma_f32_16x16x32_bf16 v[92:95], v[28:31], v[28:31], 0
	v_mfma_f32_16x16x32_bf16 v[96:99], v[28:31], v[28:31], 0
	v_mfma_f32_16x16x32_bf16 v[100:103], v[28:31], v[28:31], 0
	v_mfma_f32_16x16x32_bf16 v[104:107], v[28:31], v[28:31], 0
	v_mfma_f32_16x16x32_bf16 v[108:111], v[28:31], v[28:31], 0
	v_mfma_f32_16x16x32_bf16 v[112:115], v[28:31], v[28:31], 0
	v_mfma_f32_16x16x32_bf16 v[116:119], v[28:31], v[28:31], 0
	v_mfma_f32_16x16x32_bf16 v[120:123], v[28:31], v[28:31], 0
	v_mfma_f32_16x16x32_bf16 v[124:127], v[28:31], v[28:31], 0
	v_mfma_f32_16x16x32_bf16 v[128:131], v[28:31], v[28:31], 0
	v_mfma_f32_16x16x32_bf16 v[132:135], v[28:31], v[28:31], 0
	v_mfma_f32_16x16x32_bf16 v[136:139], v[28:31], v[28:31], 0
	v_mfma_f32_16x16x32_bf16 v[140:143], v[28:31], v[28:31], 0
